# grid barrier acquire hoisting: the per-CU L1 invalidate (buffer_inv sc1) is issued before the spin on the release flag instead of after it (no wave of the CU can refill L1 while thread 0 spins with sc
# speedup vs baseline: 1.0161x; 1.0161x over previous
; __device__ __forceinline__ unsigned xb_ld(unsigned* p)              { return __hip_atomic_load(p, __ATOMIC_RELAXED, __HIP_MEMORY_SCOPE_AGENT); }
; __device__ __forceinline__ unsigned xb_add(unsigned* p, unsigned v) { return __hip_atomic_fetch_add(p, v, __ATOMIC_RELAXED, __HIP_MEMORY_SCOPE_AGENT); }
; #define XB_SPIN(cond, bar) do { unsigned _sp = 0; while (cond) { __builtin_amdgcn_s_sleep(1); \
;     if ((++_sp & 255u) == 0u) { if (xb_ld(&(bar)[XB_TMO])) break; if (_sp > XB_SPIN_CAP) { atomicAdd(&(bar)[XB_TMO], 1u); break; } } } } while (0)
; __device__ __forceinline__ void xcd_barrier(const XcdBarrier& b) {
;     ...
;         const unsigned old = xb_add(&bar[XB_XSUB(b.x)], 1u);
;         const unsigned gen = old / nloc;
;         if (old + 1u == (gen + 1u) * nloc) {
;             __builtin_amdgcn_fence(__ATOMIC_RELEASE, "agent");
;             asm volatile("s_waitcnt vmcnt(0)" ::: "memory");
;             const unsigned og = xb_add(&bar[XB_TOP], 1u);
;             const unsigned tg = og / nx;
;             if (og + 1u == (tg + 1u) * nx) xb_add(&bar[XB_TOPGEN], 1u);
;             else XB_SPIN(xb_ld(&bar[XB_TOPGEN]) == tg, bar);
;             __builtin_amdgcn_fence(__ATOMIC_ACQUIRE, "agent");
;             xb_add(&bar[XB_XGEN(b.x)], 1u);
;             asm volatile("s_waitcnt vmcnt(0)" ::: "memory");
;         } else {
;             XB_SPIN(xb_ld(&bar[XB_XGEN(b.x)]) == gen, bar);
.LBB0_809:
	s_or_b64 exec, exec, s[40:41]
	v_cvt_f32_u32_e32 v9, v3
	s_waitcnt vmcnt(0)
	v_readfirstlane_b32 s15, v8
	v_sub_u32_e32 v8, 0, v3
	v_rcp_iflag_f32_e32 v9, v9
	v_add_u32_e32 v10, s15, v0
	v_mul_f32_e32 v9, 0x4f7ffffe, v9
	v_cvt_u32_f32_e32 v9, v9
	v_mul_lo_u32 v0, v8, v9
	v_mul_hi_u32 v0, v9, v0
	v_add_u32_e32 v0, v9, v0
	v_mul_hi_u32 v0, v10, v0
	v_mul_lo_u32 v8, v0, v3
	v_sub_u32_e32 v8, v10, v8
	v_add_u32_e32 v9, 1, v0
	v_cmp_ge_u32_e32 vcc, v8, v3
	s_nop 1
	v_cndmask_b32_e32 v0, v0, v9, vcc
	v_sub_u32_e32 v9, v8, v3
	v_cndmask_b32_e32 v8, v8, v9, vcc
	v_add_u32_e32 v9, 1, v0
	v_cmp_ge_u32_e32 vcc, v8, v3
	v_add_u32_e32 v8, 1, v10
	s_nop 0
	v_cndmask_b32_e32 v0, v0, v9, vcc
	v_mul_lo_u32 v9, v3, v0
	v_add_u32_e32 v3, v9, v3
	v_cmp_ne_u32_e32 vcc, v8, v3
	s_and_saveexec_b64 s[24:25], vcc
	s_xor_b64 s[40:41], exec, s[24:25]
	s_cbranch_execz .LBB0_823
	v_readlane_b32 s24, v253, 57
	v_readlane_b32 s25, v253, 58
	s_waitcnt lgkmcnt(0)
	s_nop 3
	buffer_inv sc1
	global_load_dword v2, v1, s[24:25] sc1
	s_waitcnt vmcnt(0)
	v_cmp_eq_u32_e32 vcc, v2, v0
	s_and_saveexec_b64 s[42:43], vcc
	s_cbranch_execz .LBB0_822
	s_mov_b32 s15, 1
	s_mov_b64 s[44:45], 0
	s_branch .LBB0_813

; __device__ __forceinline__ unsigned xb_ld(unsigned* p)              { return __hip_atomic_load(p, __ATOMIC_RELAXED, __HIP_MEMORY_SCOPE_AGENT); }
; #define XB_SPIN(cond, bar) do { unsigned _sp = 0; while (cond) { __builtin_amdgcn_s_sleep(1); \
;     if ((++_sp & 255u) == 0u) { if (xb_ld(&(bar)[XB_TMO])) break; if (_sp > XB_SPIN_CAP) { atomicAdd(&(bar)[XB_TMO], 1u); break; } } } } while (0)
; __device__ __forceinline__ void xcd_barrier(const XcdBarrier& b) {
;     ...
;         } else {
;             XB_SPIN(xb_ld(&bar[XB_XGEN(b.x)]) == gen, bar);
;             __builtin_amdgcn_fence(__ATOMIC_ACQUIRE, "agent");
;             asm volatile("s_waitcnt vmcnt(0)" ::: "memory");
.LBB0_822:
	s_or_b64 exec, exec, s[42:43]
	s_waitcnt vmcnt(0)
	s_waitcnt vmcnt(0)

; __device__ __forceinline__ unsigned xb_ld(unsigned* p)              { return __hip_atomic_load(p, __ATOMIC_RELAXED, __HIP_MEMORY_SCOPE_AGENT); }
; __device__ __forceinline__ unsigned xb_add(unsigned* p, unsigned v) { return __hip_atomic_fetch_add(p, v, __ATOMIC_RELAXED, __HIP_MEMORY_SCOPE_AGENT); }
; #define XB_SPIN(cond, bar) do { unsigned _sp = 0; while (cond) { __builtin_amdgcn_s_sleep(1); \
;     if ((++_sp & 255u) == 0u) { if (xb_ld(&(bar)[XB_TMO])) break; if (_sp > XB_SPIN_CAP) { atomicAdd(&(bar)[XB_TMO], 1u); break; } } } } while (0)
; __device__ __forceinline__ void xcd_barrier(const XcdBarrier& b) {
;     ...
;         if (old + 1u == (gen + 1u) * nloc) {
;             __builtin_amdgcn_fence(__ATOMIC_RELEASE, "agent");
;             asm volatile("s_waitcnt vmcnt(0)" ::: "memory");
;             const unsigned og = xb_add(&bar[XB_TOP], 1u);
;             const unsigned tg = og / nx;
;             if (og + 1u == (tg + 1u) * nx) xb_add(&bar[XB_TOPGEN], 1u);
;             else XB_SPIN(xb_ld(&bar[XB_TOPGEN]) == tg, bar);
;             __builtin_amdgcn_fence(__ATOMIC_ACQUIRE, "agent");
.LBB0_826:
	s_or_b64 exec, exec, s[42:43]
	buffer_inv sc1
	s_waitcnt vmcnt(1)
	v_readfirstlane_b32 s15, v3
	v_sub_u32_e32 v8, 0, v2
	v_readlane_b32 s24, v253, 61
	v_add_u32_e32 v3, s15, v0
	v_cvt_f32_u32_e32 v0, v2
	v_readlane_b32 s25, v253, 62
	s_mov_b64 s[42:43], -1
	v_rcp_iflag_f32_e32 v0, v0
	s_nop 0
	v_mul_f32_e32 v0, 0x4f7ffffe, v0
	v_cvt_u32_f32_e32 v0, v0
	v_mul_lo_u32 v8, v8, v0
	v_mul_hi_u32 v8, v0, v8
	v_add_u32_e32 v0, v0, v8
	v_mul_hi_u32 v0, v3, v0
	v_mul_lo_u32 v8, v0, v2
	v_sub_u32_e32 v8, v3, v8
	v_cmp_ge_u32_e32 vcc, v8, v2
	v_add_u32_e32 v9, 1, v0
	v_add_u32_e32 v3, 1, v3
	v_cndmask_b32_e32 v0, v0, v9, vcc
	v_sub_u32_e32 v9, v8, v2
	v_cndmask_b32_e32 v8, v8, v9, vcc
	v_cmp_ge_u32_e32 vcc, v8, v2
	v_add_u32_e32 v8, 1, v0
	s_nop 0
	v_cndmask_b32_e32 v0, v0, v8, vcc
	v_mul_lo_u32 v8, v2, v0
	v_add_u32_e32 v2, v8, v2
	v_cmp_ne_u32_e32 vcc, v3, v2
	v_mov_b64_e32 v[2:3], s[24:25]
	s_and_saveexec_b64 s[40:41], vcc
	s_cbranch_execz .LBB0_838
	v_readlane_b32 s24, v253, 61
	v_readlane_b32 s25, v253, 62
	s_mov_b64 s[44:45], 0
	s_nop 3
	global_load_dword v2, v1, s[24:25] sc1
	s_waitcnt vmcnt(0)
	v_cmp_eq_u32_e32 vcc, v2, v0
	s_and_saveexec_b64 s[42:43], vcc
	s_cbranch_execz .LBB0_837
	s_mov_b32 s15, 1
	s_branch .LBB0_830

; __device__ __forceinline__ unsigned xb_ld(unsigned* p)              { return __hip_atomic_load(p, __ATOMIC_RELAXED, __HIP_MEMORY_SCOPE_AGENT); }
; __device__ __forceinline__ unsigned xb_add(unsigned* p, unsigned v) { return __hip_atomic_fetch_add(p, v, __ATOMIC_RELAXED, __HIP_MEMORY_SCOPE_AGENT); }
; #define XB_SPIN(cond, bar) do { unsigned _sp = 0; while (cond) { __builtin_amdgcn_s_sleep(1); \
;     if ((++_sp & 255u) == 0u) { if (xb_ld(&(bar)[XB_TMO])) break; if (_sp > XB_SPIN_CAP) { atomicAdd(&(bar)[XB_TMO], 1u); break; } } } } while (0)
; __device__ __forceinline__ void xcd_barrier(const XcdBarrier& b) {
;     ...
;             else XB_SPIN(xb_ld(&bar[XB_TOPGEN]) == tg, bar);
;             __builtin_amdgcn_fence(__ATOMIC_ACQUIRE, "agent");
;             xb_add(&bar[XB_XGEN(b.x)], 1u);
.LBB0_840:
	s_or_b64 exec, exec, s[40:41]
	s_mov_b64 s[40:41], exec
	v_mbcnt_lo_u32_b32 v0, s40, 0
	v_mbcnt_hi_u32_b32 v0, s41, v0
	v_cmp_eq_u32_e32 vcc, 0, v0
	s_and_saveexec_b64 s[42:43], vcc
	s_cbranch_execz .LBB0_19
	s_bcnt1_i32_b64 s15, s[40:41]
	v_readlane_b32 s24, v253, 57
	v_mov_b32_e32 v0, s15
	v_readlane_b32 s25, v253, 58
	s_nop 4
	global_atomic_add v1, v0, s[24:25]
	s_branch .LBB0_19
